# stagger: workgroups with blockIdx bit 8 set start each GEMM phase ~1280 cycles later so the two workgroups of a CU run their k-steps out of phase
# speedup vs baseline: 1.0165x; 1.0003x over previous
.LBB0_220:
	s_or_b64 exec, exec, s[34:35]
	v_readlane_b32 s0, v254, 20
	v_readlane_b32 s1, v254, 21
	v_mov_b32_e32 v2, v188
	s_andn2_b64 vcc, exec, s[0:1]
	s_waitcnt lgkmcnt(0)
	s_barrier
	s_cselect_b32 s99, 1, 0
	v_readlane_b32 s98, v253, 4
	s_nop 3
	s_bitcmp1_b32 s98, 8
	s_cbranch_scc0 .Lnosleep_0
	s_sleep 20
.Lnosleep_0:
	s_cmp_lg_u32 s99, 0
	s_cbranch_vccnz .LBB0_245
	s_mul_i32 s0, s58, 0x280000
	v_readlane_b32 s1, v254, 22
	s_add_u32 s34, s1, s0
	v_readlane_b32 s0, v254, 23
	s_addc_u32 s35, s0, 0
	v_and_b32_e32 v3, 63, v2
	v_ashrrev_i32_e32 v20, 6, v2
	v_readlane_b32 s0, v254, 28
	v_bfe_u32 v21, v2, 3, 3
	v_readlane_b32 s1, v254, 29
	s_add_u32 s0, s34, s0
	v_bitop3_b32 v0, v21, v2, 7 bitop3:0x78
	v_readlane_b32 s2, v254, 26
	v_lshl_add_u32 v95, v3, 4, 0
	v_lshl_or_b32 v8, v20, 5, v21
	s_addc_u32 s1, s35, s1
	v_lshlrev_b32_e32 v0, 4, v0
	v_readlane_b32 s3, v254, 27
	v_ashrrev_i32_e32 v9, 31, v8
	v_lshl_add_u32 v138, v20, 12, v95
	v_lshlrev_b32_e32 v22, 2, v20
	v_lshl_add_u64 v[4:5], s[2:3], 0, v[0:1]
	v_lshl_add_u64 v[6:7], s[0:1], 0, v[0:1]
	v_lshlrev_b64 v[10:11], 11, v[8:9]
	v_readfirstlane_b32 s0, v138
	v_lshl_add_u64 v[12:13], v[4:5], 0, v[10:11]
	v_add_u32_e32 v139, 0x8000, v138
	s_mov_b32 m0, s0
	v_or_b32_e32 v3, 1, v22
	global_load_lds_dwordx4 v[12:13], off
	v_readfirstlane_b32 s0, v139
	v_lshl_or_b32 v12, v3, 3, v21
	v_lshl_add_u64 v[14:15], v[6:7], 0, v[10:11]
	s_mov_b32 m0, s0
	v_ashrrev_i32_e32 v13, 31, v12
	v_lshl_add_u32 v140, v3, 10, v95
	global_load_lds_dwordx4 v[14:15], off
	v_lshlrev_b64 v[14:15], 11, v[12:13]
	v_add_u32_e32 v141, 0x8000, v140
	v_readfirstlane_b32 s0, v140
	v_lshl_add_u64 v[16:17], v[4:5], 0, v[14:15]
	s_mov_b32 m0, s0
	v_readfirstlane_b32 s0, v141
	v_lshl_add_u64 v[14:15], v[6:7], 0, v[14:15]
	global_load_lds_dwordx4 v[16:17], off
	s_mov_b32 m0, s0
	v_or_b32_e32 v23, 2, v22
	global_load_lds_dwordx4 v[14:15], off
	v_lshl_or_b32 v14, v23, 3, v21
	v_ashrrev_i32_e32 v15, 31, v14
	v_lshl_add_u32 v142, v23, 10, v95
	v_lshlrev_b64 v[16:17], 11, v[14:15]
	v_add_u32_e32 v143, 0x8000, v142
	v_readfirstlane_b32 s0, v142
	v_lshl_add_u64 v[18:19], v[4:5], 0, v[16:17]
	s_mov_b32 m0, s0
	v_readfirstlane_b32 s0, v143
	v_lshl_add_u64 v[16:17], v[6:7], 0, v[16:17]
	global_load_lds_dwordx4 v[18:19], off
	s_mov_b32 m0, s0
	v_or_b32_e32 v22, 3, v22
	global_load_lds_dwordx4 v[16:17], off
	v_lshl_or_b32 v16, v22, 3, v21
	v_ashrrev_i32_e32 v17, 31, v16
	v_lshl_add_u32 v144, v22, 10, v95
	v_lshlrev_b64 v[18:19], 11, v[16:17]
	v_add_u32_e32 v145, 0x8000, v144
	v_readfirstlane_b32 s0, v144
	v_lshl_add_u64 v[4:5], v[4:5], 0, v[18:19]
	s_mov_b32 m0, s0
	v_readfirstlane_b32 s0, v145
	v_lshl_add_u64 v[6:7], v[6:7], 0, v[18:19]
	global_load_lds_dwordx4 v[4:5], off
	s_mov_b32 m0, s0
	v_and_b32_e32 v146, 15, v2
	global_load_lds_dwordx4 v[6:7], off
	v_bfe_u32 v18, v2, 4, 2
	v_ashrrev_i32_e32 v21, 7, v2
	v_and_b32_e32 v19, 1, v20
	v_and_b32_e32 v24, 7, v2
	v_lshlrev_b64 v[4:5], 10, v[8:9]
	v_lshlrev_b32_e32 v148, 9, v3
	v_lshlrev_b32_e32 v3, 13, v21
	v_lshlrev_b32_e32 v9, 7, v146
	v_bitop3_b32 v2, v18, v2, 7 bitop3:0x78
	v_add3_u32 v151, 0, v3, v9
	v_lshlrev_b32_e32 v3, 13, v19
	v_lshlrev_b32_e32 v157, 4, v2
	v_bitop3_b32 v2, v18, v24, 4 bitop3:0x36
	v_add3_u32 v152, 0, v3, v9
	v_lshlrev_b32_e32 v158, 4, v2
	v_lshl_or_b32 v2, v18, 5, v9
	v_mov_b32_e32 v3, v1
	v_lshlrev_b64 v[6:7], 10, v[12:13]
	v_lshlrev_b64 v[12:13], 10, v[14:15]
	v_lshlrev_b64 v[14:15], 10, v[16:17]
	v_readlane_b32 s0, v253, 40
	v_lshl_add_u64 v[96:97], s[16:17], 0, v[2:3]
	v_or_b32_e32 v2, 8, v8
	v_or_b32_e32 v16, 16, v8
	v_or_b32_e32 v8, 24, v8
	v_readlane_b32 s1, v253, 41
	v_ashrrev_i32_e32 v3, 31, v2
	v_ashrrev_i32_e32 v17, 31, v16
	v_ashrrev_i32_e32 v9, 31, v8
	v_lshl_add_u64 v[90:91], s[0:1], 0, v[0:1]
	v_readlane_b32 s0, v254, 44
	v_lshlrev_b64 v[2:3], 11, v[2:3]
	v_lshlrev_b64 v[16:17], 11, v[16:17]
	v_lshlrev_b64 v[8:9], 11, v[8:9]
	v_or_b32_e32 v10, v10, v0
	v_readlane_b32 s1, v254, 45
	v_or_b32_e32 v2, v2, v0
	v_or_b32_e32 v16, v16, v0
	v_or_b32_e32 v8, v8, v0
	v_lshl_add_u64 v[98:99], s[0:1], 0, v[10:11]
	v_lshl_add_u64 v[100:101], s[0:1], 0, v[2:3]
	v_lshl_add_u64 v[102:103], s[0:1], 0, v[16:17]
	v_lshl_add_u64 v[104:105], s[0:1], 0, v[8:9]
	v_readlane_b32 s0, v254, 46
	s_lshl_b32 s60, s58, 6
	v_lshlrev_b32_e32 v94, 2, v18
	v_lshlrev_b32_e32 v154, 6, v21
	v_readlane_b32 s1, v254, 47
	v_lshlrev_b32_e32 v147, 11, v20
	v_lshlrev_b32_e32 v149, 9, v23
	v_lshlrev_b32_e32 v150, 9, v22
	v_lshl_add_u64 v[92:93], s[34:35], 0, v[0:1]
	v_lshlrev_b32_e32 v153, 6, v19
	v_or_b32_e32 v155, v154, v146
	v_or_b32_e32 v156, 0xfffffb80, v94
	v_lshl_add_u64 v[106:107], s[0:1], 0, v[10:11]
	v_lshl_add_u64 v[108:109], s[0:1], 0, v[2:3]
	v_lshl_add_u64 v[110:111], s[0:1], 0, v[16:17]
	v_lshl_add_u64 v[112:113], s[0:1], 0, v[8:9]
	v_lshlrev_b64 v[114:115], 1, v[4:5]
	v_lshlrev_b64 v[116:117], 1, v[6:7]
	v_lshlrev_b64 v[118:119], 1, v[12:13]
	v_lshlrev_b64 v[120:121], 1, v[14:15]
	s_lshl_b64 s[34:35], s[60:61], 2
	s_mov_b32 s33, 0x800000
	v_readlane_b32 s0, v253, 4
	s_waitcnt vmcnt(0)
	s_branch .LBB0_223

.LBB0_886:
	s_or_b64 exec, exec, s[34:35]
	s_lshr_b32 s23, s22, 4
	s_cmp_lt_i32 s56, s23
	s_waitcnt lgkmcnt(0)
	v_mov_b32_e32 v2, v188
	s_cselect_b64 s[38:39], -1, 0
	s_cmp_ge_i32 s56, s23
	s_barrier
	s_cselect_b32 s99, 1, 0
	v_readlane_b32 s98, v253, 4
	s_nop 3
	s_bitcmp1_b32 s98, 8
	s_cbranch_scc0 .Lnosleep_1
	s_sleep 20
.Lnosleep_1:
	s_cmp_lg_u32 s99, 0
	s_cbranch_scc1 .LBB0_895
	s_lshl_b32 s0, s58, 21
	v_readlane_b32 s1, v254, 38
	s_add_u32 s34, s1, s0
	v_readlane_b32 s0, v254, 39
	s_addc_u32 s35, s0, 0
	s_lshr_b32 s2, s22, 7
	v_readlane_b32 s0, v254, 24
	s_mul_i32 s0, s2, s0
	v_readlane_b32 s1, v254, 25
	s_add_i32 s0, s0, s1
	s_ashr_i32 s1, s0, 31
	s_lshr_b32 s1, s1, 26
	s_add_i32 s1, s0, s1
	s_and_b32 s3, s1, 0xffffffc0
	s_sub_i32 s3, s0, s3
	s_lshl_b32 s0, s1, 4
	s_lshl_b32 s1, s3, 7
	s_and_b32 s0, s0, 0xfffffc00
	s_and_b32 s1, s1, 0x380
	s_or_b32 s0, s1, s0
	s_lshl_b32 s1, s3, 4
	s_and_b32 s26, s1, 0xffffff80
	s_ashr_i32 s1, s0, 31
	s_lshl_b64 s[0:1], s[0:1], 11
	v_readlane_b32 s36, v254, 32
	v_and_b32_e32 v3, 63, v2
	v_ashrrev_i32_e32 v20, 6, v2
	v_readlane_b32 s37, v254, 33
	s_add_u32 s0, s36, s0
	v_bfe_u32 v21, v2, 3, 3
	s_addc_u32 s1, s37, s1
	s_ashr_i32 s27, s26, 31
	v_bitop3_b32 v0, v21, v2, 7 bitop3:0x78
	v_lshl_add_u32 v112, v3, 4, 0
	v_lshl_or_b32 v8, v20, 5, v21
	s_lshl_b64 s[26:27], s[26:27], 11
	v_lshlrev_b32_e32 v0, 4, v0
	v_ashrrev_i32_e32 v9, 31, v8
	v_lshl_add_u32 v113, v20, 12, v112
	s_add_u32 s26, s34, s26
	v_lshlrev_b32_e32 v22, 2, v20
	v_lshl_add_u64 v[4:5], s[0:1], 0, v[0:1]
	v_lshlrev_b64 v[10:11], 11, v[8:9]
	v_readfirstlane_b32 s0, v113
	s_addc_u32 s27, s35, s27
	v_lshl_add_u64 v[12:13], v[4:5], 0, v[10:11]
	v_add_u32_e32 v114, 0x8000, v113
	s_mov_b32 m0, s0
	v_or_b32_e32 v3, 1, v22
	v_lshl_add_u64 v[6:7], s[26:27], 0, v[0:1]
	global_load_lds_dwordx4 v[12:13], off
	v_readfirstlane_b32 s0, v114
	v_lshl_or_b32 v12, v3, 3, v21
	v_lshl_add_u64 v[14:15], v[6:7], 0, v[10:11]
	s_mov_b32 m0, s0
	v_ashrrev_i32_e32 v13, 31, v12
	v_lshl_add_u32 v115, v3, 10, v112
	global_load_lds_dwordx4 v[14:15], off
	v_lshlrev_b64 v[14:15], 11, v[12:13]
	v_add_u32_e32 v116, 0x8000, v115
	v_readfirstlane_b32 s0, v115
	v_lshl_add_u64 v[16:17], v[4:5], 0, v[14:15]
	s_mov_b32 m0, s0
	v_readfirstlane_b32 s0, v116
	v_lshl_add_u64 v[14:15], v[6:7], 0, v[14:15]
	global_load_lds_dwordx4 v[16:17], off
	s_mov_b32 m0, s0
	v_or_b32_e32 v23, 2, v22
	global_load_lds_dwordx4 v[14:15], off
	v_lshl_or_b32 v14, v23, 3, v21
	v_ashrrev_i32_e32 v15, 31, v14
	v_lshl_add_u32 v117, v23, 10, v112
	v_lshlrev_b64 v[16:17], 11, v[14:15]
	v_add_u32_e32 v118, 0x8000, v117
	v_readfirstlane_b32 s0, v117
	v_lshl_add_u64 v[18:19], v[4:5], 0, v[16:17]
	s_mov_b32 m0, s0
	v_readfirstlane_b32 s0, v118
	v_lshl_add_u64 v[16:17], v[6:7], 0, v[16:17]
	global_load_lds_dwordx4 v[18:19], off
	s_mov_b32 m0, s0
	v_or_b32_e32 v22, 3, v22
	global_load_lds_dwordx4 v[16:17], off
	v_lshl_or_b32 v16, v22, 3, v21
	v_ashrrev_i32_e32 v17, 31, v16
	v_lshl_add_u32 v119, v22, 10, v112
	v_lshlrev_b64 v[18:19], 11, v[16:17]
	v_add_u32_e32 v120, 0x8000, v119
	v_readfirstlane_b32 s0, v119
	v_lshl_add_u64 v[4:5], v[4:5], 0, v[18:19]
	s_mov_b32 m0, s0
	v_readfirstlane_b32 s0, v120
	v_lshl_add_u64 v[6:7], v[6:7], 0, v[18:19]
	global_load_lds_dwordx4 v[4:5], off
	s_mov_b32 m0, s0
	v_bfe_u32 v19, v2, 4, 2
	global_load_lds_dwordx4 v[6:7], off
	v_and_b32_e32 v21, 15, v2
	v_ashrrev_i32_e32 v24, 7, v2
	v_and_b32_e32 v25, 7, v2
	v_bitop3_b32 v2, v19, v2, 7 bitop3:0x78
	v_and_b32_e32 v18, 1, v20
	v_lshlrev_b64 v[4:5], 10, v[8:9]
	v_lshlrev_b32_e32 v122, 9, v3
	v_lshlrev_b32_e32 v3, 13, v24
	v_lshlrev_b32_e32 v9, 7, v21
	s_waitcnt vmcnt(0)
	v_lshlrev_b32_e32 v128, 4, v2
	v_bitop3_b32 v2, v19, v25, 4 bitop3:0x36
	v_lshlrev_b32_e32 v121, 11, v20
	v_add3_u32 v125, 0, v3, v9
	v_lshlrev_b32_e32 v3, 13, v18
	v_lshlrev_b32_e32 v129, 4, v2
	v_or_b32_e32 v2, 8, v8
	v_or_b32_e32 v20, 16, v8
	v_or_b32_e32 v8, 24, v8
	v_add3_u32 v126, 0, v3, v9
	v_lshl_or_b32 v127, v24, 6, v21
	v_ashrrev_i32_e32 v3, 31, v2
	v_ashrrev_i32_e32 v21, 31, v20
	v_ashrrev_i32_e32 v9, 31, v8
	v_readlane_b32 s0, v254, 54
	v_lshlrev_b64 v[2:3], 11, v[2:3]
	v_lshlrev_b64 v[20:21], 11, v[20:21]
	v_lshlrev_b64 v[8:9], 11, v[8:9]
	v_or_b32_e32 v10, v10, v0
	v_readlane_b32 s1, v254, 55
	v_or_b32_e32 v2, v2, v0
	v_or_b32_e32 v20, v20, v0
	v_or_b32_e32 v8, v8, v0
	v_lshl_add_u64 v[70:71], s[0:1], 0, v[10:11]
	v_lshl_add_u64 v[72:73], s[0:1], 0, v[2:3]
	v_lshl_add_u64 v[74:75], s[0:1], 0, v[20:21]
	v_lshl_add_u64 v[76:77], s[0:1], 0, v[8:9]
	v_readlane_b32 s0, v254, 56
	v_lshlrev_b64 v[6:7], 10, v[12:13]
	v_lshlrev_b64 v[12:13], 10, v[14:15]
	v_lshlrev_b64 v[14:15], 10, v[16:17]
	v_lshlrev_b32_e32 v16, 6, v18
	v_lshlrev_b32_e32 v18, 2, v19
	v_readlane_b32 s1, v254, 57
	v_lshlrev_b32_e32 v123, 9, v23
	v_lshlrev_b32_e32 v124, 9, v22
	v_lshl_add_u64 v[66:67], s[36:37], 0, v[0:1]
	v_lshl_add_u64 v[68:69], s[34:35], 0, v[0:1]
	v_lshl_add_u64 v[78:79], s[0:1], 0, v[10:11]
	v_lshl_add_u64 v[80:81], s[0:1], 0, v[2:3]
	v_lshl_add_u64 v[82:83], s[0:1], 0, v[20:21]
	v_lshl_add_u64 v[84:85], s[0:1], 0, v[8:9]
	v_lshlrev_b64 v[86:87], 1, v[4:5]
	v_lshlrev_b64 v[88:89], 1, v[6:7]
	v_lshlrev_b64 v[90:91], 1, v[12:13]
	v_lshlrev_b64 v[92:93], 1, v[14:15]
	v_lshlrev_b32_e32 v0, 2, v16
	v_lshlrev_b32_e32 v94, 2, v18
	s_mov_b32 s0, s56
	s_branch .LBB0_889

.LBB0_994:
	s_or_b64 exec, exec, s[34:35]
	v_readlane_b32 s0, v253, 38
	v_readlane_b32 s1, v253, 39
	s_and_b64 s[0:1], s[0:1], exec
	s_movk_i32 s0, 0x1600
	s_cselect_b32 s2, s0, 0x18c0
	s_waitcnt lgkmcnt(0)
	v_mov_b32_e32 v2, v188
	s_cmp_ge_i32 s56, s2
	s_barrier
	s_cselect_b32 s99, 1, 0
	v_readlane_b32 s98, v253, 4
	s_nop 3
	s_bitcmp1_b32 s98, 8
	s_cbranch_scc0 .Lnosleep_2
	s_sleep 20
.Lnosleep_2:
	s_cmp_lg_u32 s99, 0
	s_cbranch_scc1 .LBB0_1004
	s_mul_i32 s0, s58, 0xb00000
	v_readlane_b32 s1, v254, 40
	s_add_u32 s34, s1, s0
	v_readlane_b32 s0, v254, 41
	s_addc_u32 s35, s0, 0
	s_lshr_b32 s3, s2, 3
	v_readlane_b32 s0, v254, 24
	s_mul_i32 s0, s3, s0
	v_readlane_b32 s1, v254, 25
	s_add_i32 s0, s0, s1
	s_mul_hi_i32 s1, s0, 0x2e8ba2e9
	s_lshr_b32 s19, s1, 31
	s_ashr_i32 s1, s1, 6
	s_add_i32 s1, s1, s19
	s_mul_i32 s19, s1, 0x160
	s_sub_i32 s19, s0, s19
	s_lshl_b32 s0, s1, 10
	s_lshl_b32 s1, s19, 7
	s_and_b32 s1, s1, 0x380
	s_or_b32 s0, s1, s0
	s_lshl_b32 s1, s19, 4
	s_and_b32 s26, s1, 0xffffff80
	s_ashr_i32 s1, s0, 31
	s_lshl_b64 s[0:1], s[0:1], 11
	v_readlane_b32 s4, v253, 40
	v_and_b32_e32 v3, 63, v2
	v_ashrrev_i32_e32 v20, 6, v2
	v_readlane_b32 s5, v253, 41
	s_add_u32 s0, s4, s0
	v_bfe_u32 v21, v2, 3, 3
	s_addc_u32 s1, s5, s1
	s_ashr_i32 s27, s26, 31
	v_bitop3_b32 v0, v21, v2, 7 bitop3:0x78
	v_lshl_add_u32 v110, v3, 4, 0
	v_lshl_or_b32 v8, v20, 5, v21
	s_lshl_b64 s[26:27], s[26:27], 11
	v_lshlrev_b32_e32 v0, 4, v0
	v_ashrrev_i32_e32 v9, 31, v8
	v_lshl_add_u32 v111, v20, 12, v110
	s_add_u32 s26, s34, s26
	v_lshlrev_b32_e32 v22, 2, v20
	v_lshl_add_u64 v[4:5], s[0:1], 0, v[0:1]
	v_lshlrev_b64 v[10:11], 11, v[8:9]
	v_readfirstlane_b32 s0, v111
	s_addc_u32 s27, s35, s27
	v_lshl_add_u64 v[12:13], v[4:5], 0, v[10:11]
	v_add_u32_e32 v112, 0x8000, v111
	s_mov_b32 m0, s0
	v_or_b32_e32 v3, 1, v22
	v_lshl_add_u64 v[6:7], s[26:27], 0, v[0:1]
	global_load_lds_dwordx4 v[12:13], off
	v_readfirstlane_b32 s0, v112
	v_lshl_or_b32 v12, v3, 3, v21
	v_lshl_add_u64 v[14:15], v[6:7], 0, v[10:11]
	s_mov_b32 m0, s0
	v_ashrrev_i32_e32 v13, 31, v12
	v_lshl_add_u32 v113, v3, 10, v110
	global_load_lds_dwordx4 v[14:15], off
	v_lshlrev_b64 v[14:15], 11, v[12:13]
	v_add_u32_e32 v114, 0x8000, v113
	v_readfirstlane_b32 s0, v113
	v_lshl_add_u64 v[16:17], v[4:5], 0, v[14:15]
	s_mov_b32 m0, s0
	v_readfirstlane_b32 s0, v114
	v_lshl_add_u64 v[14:15], v[6:7], 0, v[14:15]
	global_load_lds_dwordx4 v[16:17], off
	s_mov_b32 m0, s0
	v_or_b32_e32 v23, 2, v22
	global_load_lds_dwordx4 v[14:15], off
	v_lshl_or_b32 v14, v23, 3, v21
	v_ashrrev_i32_e32 v15, 31, v14
	v_lshl_add_u32 v115, v23, 10, v110
	v_lshlrev_b64 v[16:17], 11, v[14:15]
	v_add_u32_e32 v116, 0x8000, v115
	v_readfirstlane_b32 s0, v115
	v_lshl_add_u64 v[18:19], v[4:5], 0, v[16:17]
	s_mov_b32 m0, s0
	v_readfirstlane_b32 s0, v116
	v_lshl_add_u64 v[16:17], v[6:7], 0, v[16:17]
	global_load_lds_dwordx4 v[18:19], off
	s_mov_b32 m0, s0
	v_or_b32_e32 v22, 3, v22
	global_load_lds_dwordx4 v[16:17], off
	v_lshl_or_b32 v16, v22, 3, v21
	v_ashrrev_i32_e32 v17, 31, v16
	v_lshl_add_u32 v117, v22, 10, v110
	v_lshlrev_b64 v[18:19], 11, v[16:17]
	v_add_u32_e32 v118, 0x8000, v117
	v_readfirstlane_b32 s0, v117
	v_lshl_add_u64 v[4:5], v[4:5], 0, v[18:19]
	s_mov_b32 m0, s0
	v_readfirstlane_b32 s0, v118
	v_lshl_add_u64 v[6:7], v[6:7], 0, v[18:19]
	global_load_lds_dwordx4 v[4:5], off
	s_mov_b32 m0, s0
	v_bfe_u32 v18, v2, 4, 2
	global_load_lds_dwordx4 v[6:7], off
	v_and_b32_e32 v19, 15, v2
	v_ashrrev_i32_e32 v24, 7, v2
	v_and_b32_e32 v21, 1, v20
	v_and_b32_e32 v25, 7, v2
	v_lshlrev_b64 v[4:5], 10, v[8:9]
	v_lshlrev_b32_e32 v120, 9, v3
	v_lshlrev_b32_e32 v3, 13, v24
	v_lshlrev_b32_e32 v9, 7, v19
	v_bitop3_b32 v2, v18, v2, 7 bitop3:0x78
	v_add3_u32 v123, 0, v3, v9
	v_lshlrev_b32_e32 v3, 13, v21
	v_lshlrev_b32_e32 v127, 4, v2
	v_bitop3_b32 v2, v18, v25, 4 bitop3:0x36
	v_lshlrev_b64 v[6:7], 10, v[12:13]
	v_lshlrev_b64 v[12:13], 10, v[14:15]
	v_lshlrev_b64 v[14:15], 10, v[16:17]
	v_add3_u32 v124, 0, v3, v9
	v_lshlrev_b32_e32 v3, 2, v18
	s_waitcnt vmcnt(0)
	v_lshlrev_b32_e32 v128, 4, v2
	v_or_b32_e32 v2, 8, v8
	v_or_b32_e32 v16, 16, v8
	v_or_b32_e32 v8, 24, v8
	v_lshl_or_b32 v126, v21, 5, v3
	v_ashrrev_i32_e32 v3, 31, v2
	v_ashrrev_i32_e32 v17, 31, v16
	v_ashrrev_i32_e32 v9, 31, v8
	v_readlane_b32 s0, v254, 44
	v_lshlrev_b64 v[2:3], 11, v[2:3]
	v_lshlrev_b64 v[16:17], 11, v[16:17]
	v_lshlrev_b64 v[8:9], 11, v[8:9]
	v_or_b32_e32 v10, v10, v0
	v_readlane_b32 s1, v254, 45
	v_or_b32_e32 v2, v2, v0
	v_or_b32_e32 v16, v16, v0
	v_or_b32_e32 v8, v8, v0
	v_lshl_add_u64 v[70:71], s[0:1], 0, v[10:11]
	v_lshl_add_u64 v[72:73], s[0:1], 0, v[2:3]
	v_lshl_add_u64 v[74:75], s[0:1], 0, v[16:17]
	v_lshl_add_u64 v[76:77], s[0:1], 0, v[8:9]
	v_readlane_b32 s0, v254, 58
	v_readlane_b32 s1, v254, 59
	v_lshlrev_b32_e32 v119, 11, v20
	v_lshlrev_b32_e32 v121, 9, v23
	v_lshlrev_b32_e32 v122, 9, v22
	v_lshl_add_u64 v[66:67], s[4:5], 0, v[0:1]
	v_lshl_add_u64 v[68:69], s[34:35], 0, v[0:1]
	v_lshl_or_b32 v125, v24, 6, v19
	v_lshl_add_u64 v[78:79], s[0:1], 0, v[10:11]
	v_lshl_add_u64 v[80:81], s[0:1], 0, v[2:3]
	v_lshl_add_u64 v[82:83], s[0:1], 0, v[16:17]
	v_lshl_add_u64 v[84:85], s[0:1], 0, v[8:9]
	v_lshlrev_b64 v[86:87], 1, v[4:5]
	v_lshlrev_b64 v[88:89], 1, v[6:7]
	v_lshlrev_b64 v[90:91], 1, v[12:13]
	v_lshlrev_b64 v[92:93], 1, v[14:15]
	s_mov_b32 s0, s56
	s_movk_i32 s4, 0x1600
	s_branch .LBB0_997

.LBB0_1052:
	s_or_b64 exec, exec, s[34:35]
	s_waitcnt lgkmcnt(0)
	v_mov_b32_e32 v2, v188
	s_andn2_b64 vcc, exec, s[38:39]
	s_barrier
	s_cselect_b32 s99, 1, 0
	v_readlane_b32 s98, v253, 4
	s_nop 3
	s_bitcmp1_b32 s98, 8
	s_cbranch_scc0 .Lnosleep_3
	s_sleep 20
.Lnosleep_3:
	s_cmp_lg_u32 s99, 0
	s_cbranch_vccnz .LBB0_1061
	s_mul_i32 s0, s58, 0x580000
	v_readlane_b32 s1, v254, 42
	s_add_u32 s34, s1, s0
	v_readlane_b32 s0, v254, 43
	s_addc_u32 s35, s0, 0
	s_lshr_b32 s2, s22, 7
	v_readlane_b32 s0, v254, 24
	s_mul_i32 s0, s2, s0
	v_readlane_b32 s1, v254, 25
	s_add_i32 s0, s0, s1
	s_ashr_i32 s1, s0, 31
	s_lshr_b32 s1, s1, 26
	s_add_i32 s1, s0, s1
	s_and_b32 s3, s1, 0xffffffc0
	s_sub_i32 s0, s0, s3
	s_lshl_b32 s1, s1, 4
	s_lshl_b32 s3, s0, 7
	s_and_b32 s1, s1, 0xfffffc00
	s_and_b32 s3, s3, 0x380
	s_or_b32 s1, s3, s1
	s_lshl_b32 s0, s0, 4
	s_and_b32 s3, s0, 0xffff80
	s_mul_hi_i32 s19, s1, 0x1600
	s_mulk_i32 s1, 0x1600
	v_bfe_u32 v13, v2, 3, 3
	v_and_b32_e32 v3, 63, v2
	v_ashrrev_i32_e32 v12, 6, v2
	s_add_u32 s0, s20, s1
	v_bitop3_b32 v0, v13, v2, 7 bitop3:0x78
	s_addc_u32 s1, s21, s19
	s_mul_i32 s26, s3, 0xb00
	v_lshlrev_b32_e32 v0, 4, v0
	v_lshl_add_u32 v112, v3, 4, 0
	v_lshl_or_b32 v15, v12, 5, v13
	s_movk_i32 s3, 0xb00
	s_ashr_i32 s27, s26, 31
	v_lshl_add_u64 v[4:5], s[0:1], 0, v[0:1]
	v_mad_i64_i32 v[8:9], s[0:1], v15, s3, 0
	v_lshl_add_u32 v113, v12, 12, v112
	s_lshl_b64 s[26:27], s[26:27], 1
	v_lshlrev_b32_e32 v14, 2, v12
	v_lshlrev_b64 v[70:71], 1, v[8:9]
	v_readfirstlane_b32 s0, v113
	s_add_u32 s26, s34, s26
	v_lshl_add_u64 v[8:9], v[4:5], 0, v[70:71]
	v_add_u32_e32 v114, 0x8000, v113
	s_mov_b32 m0, s0
	v_or_b32_e32 v3, 1, v14
	s_addc_u32 s27, s35, s27
	global_load_lds_dwordx4 v[8:9], off
	v_readfirstlane_b32 s0, v114
	v_lshl_or_b32 v8, v3, 3, v13
	v_lshl_add_u64 v[6:7], s[26:27], 0, v[0:1]
	s_mov_b32 m0, s0
	v_mad_i64_i32 v[8:9], s[0:1], v8, s3, 0
	v_lshl_add_u32 v115, v3, 10, v112
	v_lshl_add_u64 v[10:11], v[6:7], 0, v[70:71]
	v_lshlrev_b64 v[72:73], 1, v[8:9]
	v_readfirstlane_b32 s0, v115
	global_load_lds_dwordx4 v[10:11], off
	v_lshl_add_u64 v[8:9], v[4:5], 0, v[72:73]
	v_add_u32_e32 v116, 0x8000, v115
	s_mov_b32 m0, s0
	v_or_b32_e32 v16, 2, v14
	global_load_lds_dwordx4 v[8:9], off
	v_readfirstlane_b32 s0, v116
	v_lshl_or_b32 v8, v16, 3, v13
	s_mov_b32 m0, s0
	v_mad_i64_i32 v[8:9], s[0:1], v8, s3, 0
	v_lshl_add_u32 v117, v16, 10, v112
	v_lshl_add_u64 v[10:11], v[6:7], 0, v[72:73]
	v_lshlrev_b64 v[74:75], 1, v[8:9]
	v_add_u32_e32 v118, 0x8000, v117
	v_readfirstlane_b32 s0, v117
	global_load_lds_dwordx4 v[10:11], off
	v_lshl_add_u64 v[8:9], v[4:5], 0, v[74:75]
	s_mov_b32 m0, s0
	v_readfirstlane_b32 s0, v118
	v_lshl_add_u64 v[10:11], v[6:7], 0, v[74:75]
	global_load_lds_dwordx4 v[8:9], off
	s_mov_b32 m0, s0
	v_lshlrev_b32_e32 v122, 9, v3
	global_load_lds_dwordx4 v[10:11], off
	v_or_b32_e32 v10, 3, v14
	v_lshl_or_b32 v8, v10, 3, v13
	v_mad_i64_i32 v[8:9], s[0:1], v8, s3, 0
	v_lshl_add_u32 v119, v10, 10, v112
	v_lshlrev_b64 v[76:77], 1, v[8:9]
	v_add_u32_e32 v120, 0x8000, v119
	v_readfirstlane_b32 s0, v119
	v_lshl_add_u64 v[4:5], v[4:5], 0, v[76:77]
	s_mov_b32 m0, s0
	v_readfirstlane_b32 s0, v120
	v_lshl_add_u64 v[6:7], v[6:7], 0, v[76:77]
	global_load_lds_dwordx4 v[4:5], off
	s_mov_b32 m0, s0
	v_ashrrev_i32_e32 v8, 7, v2
	global_load_lds_dwordx4 v[6:7], off
	v_and_b32_e32 v7, 15, v2
	v_bfe_u32 v5, v2, 4, 2
	v_and_b32_e32 v4, 1, v12
	v_lshlrev_b32_e32 v3, 13, v8
	v_lshlrev_b32_e32 v6, 7, v7
	v_and_b32_e32 v9, 7, v2
	v_add3_u32 v125, 0, v3, v6
	v_lshlrev_b32_e32 v3, 13, v4
	v_bitop3_b32 v2, v5, v2, 7 bitop3:0x78
	v_add3_u32 v126, 0, v3, v6
	v_lshlrev_b32_e32 v6, 2, v5
	v_lshlrev_b32_e32 v128, 4, v2
	v_bitop3_b32 v2, v5, v9, 4 bitop3:0x36
	s_movk_i32 s3, 0x1600
	v_or_b32_e32 v5, 8, v15
	v_lshl_or_b32 v127, v8, 6, v7
	v_mad_i64_i32 v[8:9], s[0:1], v5, s3, 0
	v_or_b32_e32 v5, 16, v15
	v_lshlrev_b32_e32 v124, 9, v10
	v_mad_i64_i32 v[10:11], s[0:1], v5, s3, 0
	v_or_b32_e32 v5, 24, v15
	v_lshlrev_b32_e32 v121, 11, v12
	v_lshlrev_b32_e32 v129, 4, v2
	v_mad_i64_i32 v[2:3], s[0:1], v15, s3, 0
	v_mad_i64_i32 v[12:13], s[0:1], v5, s3, 0
	v_readlane_b32 s26, v254, 60
	v_readlane_b32 s0, v254, 62
	v_lshlrev_b32_e32 v4, 6, v4
	v_or_b32_e32 v2, v2, v0
	v_readlane_b32 s27, v254, 61
	v_or_b32_e32 v8, v8, v0
	v_or_b32_e32 v10, v10, v0
	v_or_b32_e32 v12, v12, v0
	v_readlane_b32 s1, v254, 63
	v_lshlrev_b32_e32 v123, 9, v16
	v_lshl_add_u64 v[78:79], s[20:21], 0, v[0:1]
	v_lshl_add_u64 v[80:81], s[34:35], 0, v[0:1]
	v_lshl_add_u64 v[82:83], s[26:27], 0, v[2:3]
	v_lshl_add_u64 v[84:85], s[26:27], 0, v[8:9]
	v_lshl_add_u64 v[86:87], s[26:27], 0, v[10:11]
	v_lshl_add_u64 v[88:89], s[26:27], 0, v[12:13]
	v_lshl_add_u64 v[90:91], s[0:1], 0, v[2:3]
	v_lshl_add_u64 v[92:93], s[0:1], 0, v[8:9]
	v_lshl_add_u64 v[94:95], s[0:1], 0, v[10:11]
	v_lshl_add_u64 v[96:97], s[0:1], 0, v[12:13]
	v_lshlrev_b32_e32 v0, 2, v4
	v_lshlrev_b32_e32 v98, 2, v6
	s_mov_b32 s0, s56
	s_waitcnt vmcnt(0)
	s_branch .LBB0_1055
